# barrier: arriver at position nloc/2 of its XCD issues an early buffer_wbl2 while it waits
# baseline (speedup 1.0000x reference)
; __device__ __forceinline__ unsigned xb_ld(unsigned* p)              { return __hip_atomic_load(p, __ATOMIC_RELAXED, __HIP_MEMORY_SCOPE_AGENT); }
; __device__ __forceinline__ unsigned xb_add(unsigned* p, unsigned v) { return __hip_atomic_fetch_add(p, v, __ATOMIC_RELAXED, __HIP_MEMORY_SCOPE_AGENT); }
; #define XB_SPIN(cond, bar) do { unsigned _sp = 0; while (cond) { __builtin_amdgcn_s_sleep(1); \
;     if ((++_sp & 255u) == 0u) { if (xb_ld(&(bar)[XB_TMO])) break; if (_sp > XB_SPIN_CAP) { atomicAdd(&(bar)[XB_TMO], 1u); break; } } } } while (0)
; __device__ __forceinline__ void xcd_barrier(const XcdBarrier& b, int wv) {
;     ...
;         const unsigned old = xb_add(&bar[XB_XSUB(bx)], 1u);
;         const unsigned gen = old / nloc;
;         if (old + 1u == (gen + 1u) * nloc) {
;             __builtin_amdgcn_fence(__ATOMIC_RELEASE, "agent");
;             asm volatile("s_waitcnt vmcnt(0)" ::: "memory");
;             const unsigned og = xb_add(&bar[XB_TOP], 1u);
;             const unsigned tg = og / nx;
;             if (og + 1u == (tg + 1u) * nx) xb_add(&bar[XB_TOPGEN], 1u);
;             else XB_SPIN(xb_ld(&bar[XB_TOPGEN]) == tg, bar);
;             __builtin_amdgcn_fence(__ATOMIC_ACQUIRE, "agent");
;             xb_add(&bar[XB_XGEN(bx)], 1u);
;             asm volatile("s_waitcnt vmcnt(0)" ::: "memory");
;         } else {
;             XB_SPIN(xb_ld(&bar[XB_XGEN(bx)]) == gen, bar);
.LBB0_142:
	s_or_b64 exec, exec, s[6:7]
	v_cvt_f32_u32_e32 v4, v2
	s_waitcnt vmcnt(1)
	v_readfirstlane_b32 s4, v3
	v_sub_u32_e32 v3, 0, v2
	v_rcp_iflag_f32_e32 v4, v4
	v_add_u32_e32 v5, s4, v1
	v_mul_f32_e32 v4, 0x4f7ffffe, v4
	v_cvt_u32_f32_e32 v4, v4
	v_mul_lo_u32 v1, v3, v4
	v_mul_hi_u32 v1, v4, v1
	v_add_u32_e32 v1, v4, v1
	v_mul_hi_u32 v1, v5, v1
	v_mul_lo_u32 v3, v1, v2
	v_sub_u32_e32 v3, v5, v3
	v_add_u32_e32 v4, 1, v1
	v_cmp_ge_u32_e32 vcc, v3, v2
	s_nop 1
	v_cndmask_b32_e32 v1, v1, v4, vcc
	v_sub_u32_e32 v4, v3, v2
	v_cndmask_b32_e32 v3, v3, v4, vcc
	v_add_u32_e32 v4, 1, v1
	v_cmp_ge_u32_e32 vcc, v3, v2
	v_add_u32_e32 v3, 1, v5
	s_nop 0
	v_cndmask_b32_e32 v1, v1, v4, vcc
	v_mul_lo_u32 v4, v2, v1
	v_add_u32_e32 v2, v4, v2
	v_cmp_ne_u32_e32 vcc, v3, v2
	s_and_saveexec_b64 s[4:5], vcc
	s_xor_b64 s[4:5], exec, s[4:5]
	s_cbranch_execz .LBB0_156
	s_movk_i32 s6, 0xd00
	v_lshlrev_b32_e32 v3, 1, v3
	v_sub_u32_e32 v3, v3, v4
	v_cmp_eq_u32_e32 vcc, v3, v2
	s_nop 1
	s_cbranch_vccz .Lwbe_0
	buffer_wbl2 sc1
.Lwbe_0:
	v_mad_u32_u24 v2, v1, v0, v0
	s_nop 0
	v_readfirstlane_b32 s98, v2
	s_mov_b32 s7, 0
	s_lshl_b64 s[6:7], s[6:7], 2
	s_add_u32 s10, s82, s6
	s_addc_u32 s11, s83, s7
	s_waitcnt lgkmcnt(0)
	v_mov_b32_e32 v0, 0
	global_load_dword v2, v0, s[10:11] sc1
	s_waitcnt vmcnt(0)
	v_cmp_gt_u32_e32 vcc, s98, v2
	s_and_saveexec_b64 s[6:7], vcc
	s_cbranch_execz .LBB0_155
	s_add_u32 s8, s30, 0x3e9200
	s_addc_u32 s9, s31, 0
	s_mov_b32 s36, 1
	s_mov_b64 s[12:13], 0
	s_branch .LBB0_146

; __device__ __forceinline__ unsigned xb_ld(unsigned* p)              { return __hip_atomic_load(p, __ATOMIC_RELAXED, __HIP_MEMORY_SCOPE_AGENT); }
; __device__ __forceinline__ unsigned xb_add(unsigned* p, unsigned v) { return __hip_atomic_fetch_add(p, v, __ATOMIC_RELAXED, __HIP_MEMORY_SCOPE_AGENT); }
; #define XB_SPIN(cond, bar) do { unsigned _sp = 0; while (cond) { __builtin_amdgcn_s_sleep(1); \
;     if ((++_sp & 255u) == 0u) { if (xb_ld(&(bar)[XB_TMO])) break; if (_sp > XB_SPIN_CAP) { atomicAdd(&(bar)[XB_TMO], 1u); break; } } } } while (0)
; __device__ __forceinline__ void xcd_barrier(const XcdBarrier& b, int wv) {
;     ...
;         const unsigned old = xb_add(&bar[XB_XSUB(bx)], 1u);
;         const unsigned gen = old / nloc;
;         if (old + 1u == (gen + 1u) * nloc) {
;             __builtin_amdgcn_fence(__ATOMIC_RELEASE, "agent");
;             asm volatile("s_waitcnt vmcnt(0)" ::: "memory");
;             const unsigned og = xb_add(&bar[XB_TOP], 1u);
;             const unsigned tg = og / nx;
;             if (og + 1u == (tg + 1u) * nx) xb_add(&bar[XB_TOPGEN], 1u);
;             else XB_SPIN(xb_ld(&bar[XB_TOPGEN]) == tg, bar);
;             __builtin_amdgcn_fence(__ATOMIC_ACQUIRE, "agent");
;             xb_add(&bar[XB_XGEN(bx)], 1u);
;             asm volatile("s_waitcnt vmcnt(0)" ::: "memory");
;         } else {
;             XB_SPIN(xb_ld(&bar[XB_XGEN(bx)]) == gen, bar);
.LBB0_243:
	s_or_b64 exec, exec, s[14:15]
	v_cvt_f32_u32_e32 v5, v3
	s_waitcnt vmcnt(1)
	v_readfirstlane_b32 s10, v4
	v_sub_u32_e32 v4, 0, v3
	v_rcp_iflag_f32_e32 v5, v5
	v_add_u32_e32 v6, s10, v1
	v_mul_f32_e32 v5, 0x4f7ffffe, v5
	v_cvt_u32_f32_e32 v5, v5
	v_mul_lo_u32 v1, v4, v5
	v_mul_hi_u32 v1, v5, v1
	v_add_u32_e32 v1, v5, v1
	v_mul_hi_u32 v1, v6, v1
	v_mul_lo_u32 v4, v1, v3
	v_sub_u32_e32 v4, v6, v4
	v_add_u32_e32 v5, 1, v1
	v_cmp_ge_u32_e32 vcc, v4, v3
	s_nop 1
	v_cndmask_b32_e32 v1, v1, v5, vcc
	v_sub_u32_e32 v5, v4, v3
	v_cndmask_b32_e32 v4, v4, v5, vcc
	v_add_u32_e32 v5, 1, v1
	v_cmp_ge_u32_e32 vcc, v4, v3
	v_add_u32_e32 v4, 1, v6
	s_nop 0
	v_cndmask_b32_e32 v1, v1, v5, vcc
	v_mul_lo_u32 v5, v3, v1
	v_add_u32_e32 v3, v5, v3
	v_cmp_ne_u32_e32 vcc, v4, v3
	s_and_saveexec_b64 s[10:11], vcc
	s_xor_b64 s[10:11], exec, s[10:11]
	s_cbranch_execz .LBB0_257
	s_movk_i32 s36, 0xd00
	v_lshlrev_b32_e32 v4, 1, v4
	v_sub_u32_e32 v4, v4, v5
	v_cmp_eq_u32_e32 vcc, v4, v3
	s_nop 1
	s_cbranch_vccz .Lwbe_1
	buffer_wbl2 sc1
.Lwbe_1:
	v_mad_u32_u24 v2, v1, v2, v2
	s_nop 0
	v_readfirstlane_b32 s98, v2
	s_lshl_b64 s[14:15], s[36:37], 2
	s_add_u32 s16, s82, s14
	s_addc_u32 s17, s83, s15
	s_waitcnt lgkmcnt(0)
	global_load_dword v2, v0, s[16:17] sc1
	s_waitcnt vmcnt(0)
	v_cmp_gt_u32_e32 vcc, s98, v2
	s_and_saveexec_b64 s[14:15], vcc
	s_cbranch_execz .LBB0_256
	s_mov_b32 s36, 1
	s_mov_b64 s[20:21], 0
	s_branch .LBB0_247

; __device__ __forceinline__ unsigned xb_ld(unsigned* p)              { return __hip_atomic_load(p, __ATOMIC_RELAXED, __HIP_MEMORY_SCOPE_AGENT); }
; __device__ __forceinline__ unsigned xb_add(unsigned* p, unsigned v) { return __hip_atomic_fetch_add(p, v, __ATOMIC_RELAXED, __HIP_MEMORY_SCOPE_AGENT); }
; #define XB_SPIN(cond, bar) do { unsigned _sp = 0; while (cond) { __builtin_amdgcn_s_sleep(1); \
;     if ((++_sp & 255u) == 0u) { if (xb_ld(&(bar)[XB_TMO])) break; if (_sp > XB_SPIN_CAP) { atomicAdd(&(bar)[XB_TMO], 1u); break; } } } } while (0)
; __device__ __forceinline__ void xcd_barrier(const XcdBarrier& b, int wv) {
;     ...
;         const unsigned old = xb_add(&bar[XB_XSUB(bx)], 1u);
;         const unsigned gen = old / nloc;
;         if (old + 1u == (gen + 1u) * nloc) {
;             __builtin_amdgcn_fence(__ATOMIC_RELEASE, "agent");
;             asm volatile("s_waitcnt vmcnt(0)" ::: "memory");
;             const unsigned og = xb_add(&bar[XB_TOP], 1u);
;             const unsigned tg = og / nx;
;             if (og + 1u == (tg + 1u) * nx) xb_add(&bar[XB_TOPGEN], 1u);
;             else XB_SPIN(xb_ld(&bar[XB_TOPGEN]) == tg, bar);
;             __builtin_amdgcn_fence(__ATOMIC_ACQUIRE, "agent");
;             xb_add(&bar[XB_XGEN(bx)], 1u);
;             asm volatile("s_waitcnt vmcnt(0)" ::: "memory");
;         } else {
;             XB_SPIN(xb_ld(&bar[XB_XGEN(bx)]) == gen, bar);
.LBB0_351:
	s_or_b64 exec, exec, s[10:11]
	v_cvt_f32_u32_e32 v5, v3
	s_waitcnt vmcnt(1)
	v_readfirstlane_b32 s6, v4
	v_sub_u32_e32 v4, 0, v3
	v_rcp_iflag_f32_e32 v5, v5
	v_add_u32_e32 v6, s6, v1
	v_mul_f32_e32 v5, 0x4f7ffffe, v5
	v_cvt_u32_f32_e32 v5, v5
	v_mul_lo_u32 v1, v4, v5
	v_mul_hi_u32 v1, v5, v1
	v_add_u32_e32 v1, v5, v1
	v_mul_hi_u32 v1, v6, v1
	v_mul_lo_u32 v4, v1, v3
	v_sub_u32_e32 v4, v6, v4
	v_add_u32_e32 v5, 1, v1
	v_cmp_ge_u32_e32 vcc, v4, v3
	s_nop 1
	v_cndmask_b32_e32 v1, v1, v5, vcc
	v_sub_u32_e32 v5, v4, v3
	v_cndmask_b32_e32 v4, v4, v5, vcc
	v_add_u32_e32 v5, 1, v1
	v_cmp_ge_u32_e32 vcc, v4, v3
	v_add_u32_e32 v4, 1, v6
	s_nop 0
	v_cndmask_b32_e32 v1, v1, v5, vcc
	v_mul_lo_u32 v5, v3, v1
	v_add_u32_e32 v3, v5, v3
	v_cmp_ne_u32_e32 vcc, v4, v3
	s_and_saveexec_b64 s[6:7], vcc
	s_xor_b64 s[6:7], exec, s[6:7]
	s_cbranch_execz .LBB0_365
	s_movk_i32 s36, 0xd00
	v_lshlrev_b32_e32 v4, 1, v4
	v_sub_u32_e32 v4, v4, v5
	v_cmp_eq_u32_e32 vcc, v4, v3
	s_nop 1
	s_cbranch_vccz .Lwbe_2
	buffer_wbl2 sc1
.Lwbe_2:
	v_mad_u32_u24 v2, v1, v2, v2
	s_nop 0
	v_readfirstlane_b32 s98, v2
	s_lshl_b64 s[10:11], s[36:37], 2
	s_add_u32 s14, s82, s10
	s_addc_u32 s15, s83, s11
	s_waitcnt lgkmcnt(0)
	global_load_dword v2, v0, s[14:15] sc1
	s_waitcnt vmcnt(0)
	v_cmp_gt_u32_e32 vcc, s98, v2
	s_and_saveexec_b64 s[10:11], vcc
	s_cbranch_execz .LBB0_364
	s_mov_b32 s36, 1
	s_mov_b64 s[16:17], 0
	s_branch .LBB0_355

; __device__ __forceinline__ unsigned xb_ld(unsigned* p)              { return __hip_atomic_load(p, __ATOMIC_RELAXED, __HIP_MEMORY_SCOPE_AGENT); }
; __device__ __forceinline__ unsigned xb_add(unsigned* p, unsigned v) { return __hip_atomic_fetch_add(p, v, __ATOMIC_RELAXED, __HIP_MEMORY_SCOPE_AGENT); }
; #define XB_SPIN(cond, bar) do { unsigned _sp = 0; while (cond) { __builtin_amdgcn_s_sleep(1); \
;     if ((++_sp & 255u) == 0u) { if (xb_ld(&(bar)[XB_TMO])) break; if (_sp > XB_SPIN_CAP) { atomicAdd(&(bar)[XB_TMO], 1u); break; } } } } while (0)
; __device__ __forceinline__ void xcd_barrier(const XcdBarrier& b, int wv) {
;     ...
;         const unsigned old = xb_add(&bar[XB_XSUB(bx)], 1u);
;         const unsigned gen = old / nloc;
;         if (old + 1u == (gen + 1u) * nloc) {
;             __builtin_amdgcn_fence(__ATOMIC_RELEASE, "agent");
;             asm volatile("s_waitcnt vmcnt(0)" ::: "memory");
;             const unsigned og = xb_add(&bar[XB_TOP], 1u);
;             const unsigned tg = og / nx;
;             if (og + 1u == (tg + 1u) * nx) xb_add(&bar[XB_TOPGEN], 1u);
;             else XB_SPIN(xb_ld(&bar[XB_TOPGEN]) == tg, bar);
;             __builtin_amdgcn_fence(__ATOMIC_ACQUIRE, "agent");
;             xb_add(&bar[XB_XGEN(bx)], 1u);
;             asm volatile("s_waitcnt vmcnt(0)" ::: "memory");
;         } else {
;             XB_SPIN(xb_ld(&bar[XB_XGEN(bx)]) == gen, bar);
.LBB0_525:
	s_or_b64 exec, exec, s[6:7]
	v_cvt_f32_u32_e32 v5, v3
	s_waitcnt vmcnt(1)
	v_readfirstlane_b32 s4, v4
	v_sub_u32_e32 v4, 0, v3
	v_rcp_iflag_f32_e32 v5, v5
	v_add_u32_e32 v6, s4, v1
	v_mul_f32_e32 v5, 0x4f7ffffe, v5
	v_cvt_u32_f32_e32 v5, v5
	v_mul_lo_u32 v1, v4, v5
	v_mul_hi_u32 v1, v5, v1
	v_add_u32_e32 v1, v5, v1
	v_mul_hi_u32 v1, v6, v1
	v_mul_lo_u32 v4, v1, v3
	v_sub_u32_e32 v4, v6, v4
	v_add_u32_e32 v5, 1, v1
	v_cmp_ge_u32_e32 vcc, v4, v3
	s_nop 1
	v_cndmask_b32_e32 v1, v1, v5, vcc
	v_sub_u32_e32 v5, v4, v3
	v_cndmask_b32_e32 v4, v4, v5, vcc
	v_add_u32_e32 v5, 1, v1
	v_cmp_ge_u32_e32 vcc, v4, v3
	v_add_u32_e32 v4, 1, v6
	s_nop 0
	v_cndmask_b32_e32 v1, v1, v5, vcc
	v_mul_lo_u32 v5, v3, v1
	v_add_u32_e32 v3, v5, v3
	v_cmp_ne_u32_e32 vcc, v4, v3
	s_and_saveexec_b64 s[4:5], vcc
	s_xor_b64 s[4:5], exec, s[4:5]
	s_cbranch_execz .LBB0_539
	s_movk_i32 s36, 0xd00
	v_lshlrev_b32_e32 v4, 1, v4
	v_sub_u32_e32 v4, v4, v5
	v_cmp_eq_u32_e32 vcc, v4, v3
	s_nop 1
	s_cbranch_vccz .Lwbe_4
	buffer_wbl2 sc1
.Lwbe_4:
	v_mad_u32_u24 v2, v1, v2, v2
	s_nop 0
	v_readfirstlane_b32 s98, v2
	s_lshl_b64 s[6:7], s[36:37], 2
	s_add_u32 s8, s82, s6
	s_addc_u32 s9, s83, s7
	s_waitcnt lgkmcnt(0)
	global_load_dword v2, v0, s[8:9] sc1
	s_waitcnt vmcnt(0)
	v_cmp_gt_u32_e32 vcc, s98, v2
	s_and_saveexec_b64 s[6:7], vcc
	s_cbranch_execz .LBB0_538
	s_mov_b32 s36, 1
	s_mov_b64 s[10:11], 0
	s_branch .LBB0_529

; __device__ __forceinline__ unsigned xb_ld(unsigned* p)              { return __hip_atomic_load(p, __ATOMIC_RELAXED, __HIP_MEMORY_SCOPE_AGENT); }
; #define XB_SPIN(cond, bar) do { unsigned _sp = 0; while (cond) { __builtin_amdgcn_s_sleep(1); \
;     if ((++_sp & 255u) == 0u) { if (xb_ld(&(bar)[XB_TMO])) break; if (_sp > XB_SPIN_CAP) { atomicAdd(&(bar)[XB_TMO], 1u); break; } } } } while (0)
; __device__ __forceinline__ void xcd_barrier(const XcdBarrier& b, int wv) {
;     ...
;         } else {
;             XB_SPIN(xb_ld(&bar[XB_XGEN(bx)]) == gen, bar);
;             __builtin_amdgcn_fence(__ATOMIC_ACQUIRE, "agent");
;             asm volatile("s_waitcnt vmcnt(0)" ::: "memory");
.Lwbe_6:
	v_mad_u32_u24 v2, v1, v2, v2
	s_nop 0
	v_readfirstlane_b32 s98, v2
	s_lshl_b64 s[6:7], s[36:37], 2
	s_add_u32 s8, s82, s6
	s_addc_u32 s9, s83, s7
	s_waitcnt lgkmcnt(0)
	global_load_dword v2, v0, s[8:9] sc1
	s_waitcnt vmcnt(0)
	v_cmp_gt_u32_e32 vcc, s98, v2
	s_and_saveexec_b64 s[6:7], vcc
	s_cbranch_execz .LBB0_777
	s_mov_b32 s36, 1
	s_mov_b64 s[12:13], 0
	s_branch .LBB0_768

; __device__ __forceinline__ unsigned xb_ld(unsigned* p)              { return __hip_atomic_load(p, __ATOMIC_RELAXED, __HIP_MEMORY_SCOPE_AGENT); }
; __device__ __forceinline__ unsigned xb_add(unsigned* p, unsigned v) { return __hip_atomic_fetch_add(p, v, __ATOMIC_RELAXED, __HIP_MEMORY_SCOPE_AGENT); }
; #define XB_SPIN(cond, bar) do { unsigned _sp = 0; while (cond) { __builtin_amdgcn_s_sleep(1); \
;     if ((++_sp & 255u) == 0u) { if (xb_ld(&(bar)[XB_TMO])) break; if (_sp > XB_SPIN_CAP) { atomicAdd(&(bar)[XB_TMO], 1u); break; } } } } while (0)
; __device__ __forceinline__ void xcd_barrier(const XcdBarrier& b, int wv) {
;     ...
;         const unsigned old = xb_add(&bar[XB_XSUB(bx)], 1u);
;         const unsigned gen = old / nloc;
;         if (old + 1u == (gen + 1u) * nloc) {
;             __builtin_amdgcn_fence(__ATOMIC_RELEASE, "agent");
;             asm volatile("s_waitcnt vmcnt(0)" ::: "memory");
;             const unsigned og = xb_add(&bar[XB_TOP], 1u);
;             const unsigned tg = og / nx;
;             if (og + 1u == (tg + 1u) * nx) xb_add(&bar[XB_TOPGEN], 1u);
;             else XB_SPIN(xb_ld(&bar[XB_TOPGEN]) == tg, bar);
;             __builtin_amdgcn_fence(__ATOMIC_ACQUIRE, "agent");
;             xb_add(&bar[XB_XGEN(bx)], 1u);
;             asm volatile("s_waitcnt vmcnt(0)" ::: "memory");
;         } else {
;             XB_SPIN(xb_ld(&bar[XB_XGEN(bx)]) == gen, bar);
.LBB0_818:
	s_or_b64 exec, exec, s[10:11]
	v_cvt_f32_u32_e32 v8, v6
	s_waitcnt vmcnt(1)
	v_readfirstlane_b32 s8, v7
	v_sub_u32_e32 v7, 0, v6
	v_rcp_iflag_f32_e32 v8, v8
	v_add_u32_e32 v9, s8, v5
	v_mul_f32_e32 v8, 0x4f7ffffe, v8
	v_cvt_u32_f32_e32 v8, v8
	v_mul_lo_u32 v5, v7, v8
	v_mul_hi_u32 v5, v8, v5
	v_add_u32_e32 v5, v8, v5
	v_mul_hi_u32 v5, v9, v5
	v_mul_lo_u32 v7, v5, v6
	v_sub_u32_e32 v7, v9, v7
	v_add_u32_e32 v8, 1, v5
	v_cmp_ge_u32_e32 vcc, v7, v6
	s_nop 1
	v_cndmask_b32_e32 v5, v5, v8, vcc
	v_sub_u32_e32 v8, v7, v6
	v_cndmask_b32_e32 v7, v7, v8, vcc
	v_add_u32_e32 v8, 1, v5
	v_cmp_ge_u32_e32 vcc, v7, v6
	v_add_u32_e32 v7, 1, v9
	s_nop 0
	v_cndmask_b32_e32 v5, v5, v8, vcc
	v_mul_lo_u32 v8, v6, v5
	v_add_u32_e32 v6, v8, v6
	v_cmp_ne_u32_e32 vcc, v7, v6
	s_and_saveexec_b64 s[8:9], vcc
	s_xor_b64 s[8:9], exec, s[8:9]
	s_cbranch_execz .LBB0_832
	s_movk_i32 s10, 0xd00
	v_lshlrev_b32_e32 v7, 1, v7
	v_sub_u32_e32 v7, v7, v8
	v_cmp_eq_u32_e32 vcc, v7, v6
	s_nop 1
	s_cbranch_vccz .Lwbe_7
	buffer_wbl2 sc1
.Lwbe_7:
	v_mad_u32_u24 v6, v5, v4, v4
	s_nop 0
	v_readfirstlane_b32 s98, v6
	s_mov_b32 s11, 0
	s_lshl_b64 s[10:11], s[10:11], 2
	s_add_u32 s12, s82, s10
	s_addc_u32 s13, s83, s11
	s_waitcnt lgkmcnt(0)
	v_mov_b32_e32 v4, 0
	global_load_dword v6, v4, s[12:13] sc1
	s_waitcnt vmcnt(0)
	v_cmp_gt_u32_e32 vcc, s98, v6
	s_and_saveexec_b64 s[10:11], vcc
	s_cbranch_execz .LBB0_831
	s_mov_b32 s25, 1
	s_mov_b64 s[14:15], 0
	s_branch .LBB0_822
